# v16 plus 64-byte alignment of the three GEMM K-loop heads and the attention item-loop head (code placement)
# baseline (speedup 1.0000x reference)
; __device__ __forceinline__ void attn_phase(LAS unsigned char* lds, bf16* Qb, const bf16* Kb, const bf16* Vb, const float* rpb_l, int seq_len, int G, int bx, int tid, int wave, int lane) {
;     ...
;     for (int loc = lc; loc < per; loc += nx) {
;     ...
;         const int nloc = loc + nx; const bool has_next = nloc < per;
.LBB0_95:
	s_and_b64 vcc, exec, s[12:13]
	s_mov_b32 s62, s60
	s_mov_b32 s63, s61
	s_cbranch_vccnz .LBB0_103
	.p2align	6

; #define PG8_STAGE(bufoff, gbase, voff) do { _Pragma("unroll") for (int _i = 0; _i < 2; ++_i) \
;         __builtin_amdgcn_global_load_lds((const unsigned*)((const char*)(gbase) + (voff)[_i]), (PG8_LAS unsigned*)(lds + (bufoff) + ldsw + _i * 8192), 16, 0, 0); } while (0)
; #define PG8_LDA(dst, b, h) do { _Pragma("unroll") for (int m = 0; m < 4; ++m) _Pragma("unroll") for (int k = 0; k < 2; ++k) dst[m][k] = *(const PG8_LAS bf16x8*)(lds + PG8_SA(b, h) + aoff + m * 2048 + k * 1024); } while (0)
; #define PG8_LDB(dst, b, h) do { _Pragma("unroll") for (int n = 0; n < 2; ++n) _Pragma("unroll") for (int k = 0; k < 2; ++k) dst[n][k] = *(const PG8_LAS bf16x8*)(lds + PG8_SB(b, h) + boff + n * 2048 + k * 1024); } while (0)
; #define PG8_MMA(ai, bj, At, Bt) do { __builtin_amdgcn_s_setprio(1); _Pragma("unroll") for (int m = 0; m < 4; ++m) _Pragma("unroll") for (int n = 0; n < 2; ++n) _Pragma("unroll") for (int k = 0; k < 2; ++k) \
;         acc[ai][bj][m][n] = __builtin_amdgcn_mfma_f32_16x16x32_bf16(Bt[n][k], At[m][k], acc[ai][bj][m][n], 0, 0, 0); __builtin_amdgcn_s_setprio(0); } while (0)
; #define PG8_WAIT_V(n) asm volatile("s_waitcnt vmcnt(" #n ")" ::: "memory")
; #define PG8_WAIT_L(n) asm volatile("s_waitcnt lgkmcnt(" #n ")" ::: "memory")
; #define PG8_BAR __builtin_amdgcn_s_barrier()
; #define PG8_SCHED __builtin_amdgcn_sched_barrier(0)
; template <class Epi, class Sched, bool ALIGN_EPI = false, bool SP2 = false>
; __device__ __forceinline__ void gemm_phase(PG8_LAS unsigned char* lds, const Gemm g, const Sched& S, const Epi& E, const int tid_in) {
;     ...
;             PG8_LDB(B0, 0, 0); PG8_LDB(B1, 0, 1); PG8_SCHED; PG8_LDA(At, 0, 0); PG8_STAGE(PG8_SA(1, 1), a1 + hstepA, voffA);
;             PG8_WAIT_V(8); PG8_WAIT_L(0); PG8_BAR; PG8_MMA(0, 0, At, B0); PG8_MMA(0, 1, At, B1); PG8_BAR; PG8_SCHED;
;             PG8_LDA(At, 0, 1); PG8_STAGE(PG8_SB(0, 0), b2, voffB); PG8_STAGE(PG8_SB(0, 1), b2 + hstepB, voffB); PG8_STAGE(PG8_SA(0, 0), a2, voffA);
;             PG8_WAIT_V(8); PG8_WAIT_L(0); PG8_BAR; PG8_MMA(1, 0, At, B0); PG8_MMA(1, 1, At, B1); PG8_BAR; PG8_SCHED;
;     ...
;         for (int a = 0; a < 2; ++a)
; #pragma unroll
;             for (int b = 0; b < 2; ++b)
; #pragma unroll
;                 for (int m = 0; m < 4; ++m)
; #pragma unroll
;                     for (int n = 0; n < 2; ++n) acc[a][b][m][n] = (f32x4){0.f, 0.f, 0.f, 0.f};
.LBB0_118:
	s_andn2_b64 vcc, exec, s[18:19]
	s_cbranch_vccnz .Lzero_acc_1
	s_add_u32 s26, s26, 0x4000
	s_addc_u32 s27, s27, 0
	s_add_u32 s6, s28, 0x8000
	s_addc_u32 s7, s29, 0
	s_mov_b32 s28, 0
	s_add_i32 s40, s28, 2
	s_add_u32 s4, s26, 0x4000
	s_addc_u32 s5, s27, 0
	s_cmp_eq_u32 s58, s28
	s_cselect_b32 s34, s22, s4
	s_cselect_b32 s35, s23, s5
	s_cselect_b32 s30, s24, s6
	s_cselect_b32 s31, s25, s7
	s_add_u32 s28, s34, 0x4000
	s_addc_u32 s29, s35, 0
	s_add_i32 s4, 0, 0x10000
	s_add_i32 s41, 0, 0x14000
	v_add_u32_e32 v152, s4, v138
	v_add_u32_e32 v168, s41, v138
	ds_read_b128 v[140:143], v152
	ds_read_b128 v[144:147], v152 offset:1024
	ds_read_b128 v[148:151], v152 offset:2048
	ds_read_b128 v[152:155], v152 offset:3072
	ds_read_b128 v[156:159], v168
	ds_read_b128 v[160:163], v168 offset:1024
	ds_read_b128 v[164:167], v168 offset:2048
	ds_read_b128 v[168:171], v168 offset:3072
	v_lshl_add_u64 v[206:207], s[26:27], 0, v[132:133]
	s_add_i32 m0, s11, 0xc000
	ds_read_b128 v[172:175], v139
	ds_read_b128 v[176:179], v139 offset:1024
	ds_read_b128 v[180:183], v139 offset:2048
	ds_read_b128 v[184:187], v139 offset:3072
	ds_read_b128 v[190:193], v139 offset:4096
	ds_read_b128 v[194:197], v139 offset:5120
	ds_read_b128 v[198:201], v139 offset:6144
	ds_read_b128 v[202:205], v139 offset:7168
	global_load_lds_dwordx4 v[206:207], off
	v_lshl_add_u64 v[206:207], s[26:27], 0, v[134:135]
	s_add_i32 m0, s11, 0xe000
	s_nop 0
	global_load_lds_dwordx4 v[206:207], off
	s_waitcnt vmcnt(8)
	s_waitcnt lgkmcnt(0)
	s_barrier
	s_setprio 1
	s_waitcnt lgkmcnt(0)
	v_mfma_f32_16x16x32_bf16 v[120:123], v[140:143], v[172:175], 0
	v_mfma_f32_16x16x32_bf16 v[124:127], v[148:151], v[172:175], 0
	v_mfma_f32_16x16x32_bf16 v[108:111], v[140:143], v[180:183], 0
	v_mfma_f32_16x16x32_bf16 v[104:107], v[148:151], v[180:183], 0
	v_mfma_f32_16x16x32_bf16 v[92:95], v[140:143], v[190:193], 0
	v_mfma_f32_16x16x32_bf16 v[88:91], v[148:151], v[190:193], 0
	v_mfma_f32_16x16x32_bf16 v[76:79], v[140:143], v[198:201], 0
	v_mfma_f32_16x16x32_bf16 v[72:75], v[148:151], v[198:201], 0
	v_mfma_f32_16x16x32_bf16 v[120:123], v[144:147], v[176:179], v[120:123]
	v_mfma_f32_16x16x32_bf16 v[124:127], v[152:155], v[176:179], v[124:127]
	v_mfma_f32_16x16x32_bf16 v[108:111], v[144:147], v[184:187], v[108:111]
	v_mfma_f32_16x16x32_bf16 v[104:107], v[152:155], v[184:187], v[104:107]
	v_mfma_f32_16x16x32_bf16 v[92:95], v[144:147], v[194:197], v[92:95]
	v_mfma_f32_16x16x32_bf16 v[88:91], v[152:155], v[194:197], v[88:91]
	v_mfma_f32_16x16x32_bf16 v[76:79], v[144:147], v[202:205], v[76:79]
	v_mfma_f32_16x16x32_bf16 v[72:75], v[152:155], v[202:205], v[72:75]
	s_setprio 0
	s_setprio 1
	v_mfma_f32_16x16x32_bf16 v[116:119], v[156:159], v[172:175], 0
	v_mfma_f32_16x16x32_bf16 v[112:115], v[164:167], v[172:175], 0
	v_mfma_f32_16x16x32_bf16 v[100:103], v[156:159], v[180:183], 0
	v_mfma_f32_16x16x32_bf16 v[96:99], v[164:167], v[180:183], 0
	v_mfma_f32_16x16x32_bf16 v[84:87], v[156:159], v[190:193], 0
	v_mfma_f32_16x16x32_bf16 v[80:83], v[164:167], v[190:193], 0
	v_mfma_f32_16x16x32_bf16 v[68:71], v[156:159], v[198:201], 0
	v_mfma_f32_16x16x32_bf16 v[64:67], v[164:167], v[198:201], 0
	v_mfma_f32_16x16x32_bf16 v[116:119], v[160:163], v[176:179], v[116:119]
	v_mfma_f32_16x16x32_bf16 v[112:115], v[168:171], v[176:179], v[112:115]
	v_mfma_f32_16x16x32_bf16 v[100:103], v[160:163], v[184:187], v[100:103]
	v_mfma_f32_16x16x32_bf16 v[96:99], v[168:171], v[184:187], v[96:99]
	v_mfma_f32_16x16x32_bf16 v[84:87], v[160:163], v[194:197], v[84:87]
	v_mfma_f32_16x16x32_bf16 v[80:83], v[168:171], v[194:197], v[80:83]
	v_mfma_f32_16x16x32_bf16 v[68:71], v[160:163], v[202:205], v[68:71]
	v_mfma_f32_16x16x32_bf16 v[64:67], v[168:171], v[202:205], v[64:67]
	s_setprio 0
	s_barrier
	s_add_i32 s4, s4, s0
	v_lshl_add_u64 v[206:207], s[30:31], 0, v[128:129]
	s_mov_b32 m0, s4
	ds_read_b128 v[172:175], v139 offset:16384
	ds_read_b128 v[176:179], v139 offset:17408
	ds_read_b128 v[180:183], v139 offset:18432
	ds_read_b128 v[184:187], v139 offset:19456
	ds_read_b128 v[190:193], v139 offset:20480
	ds_read_b128 v[194:197], v139 offset:21504
	ds_read_b128 v[198:201], v139 offset:22528
	ds_read_b128 v[202:205], v139 offset:23552
	global_load_lds_dwordx4 v[206:207], off
	s_add_i32 m0, s4, 0x2000
	s_add_u32 s4, s30, s12
	v_lshl_add_u64 v[206:207], s[30:31], 0, v[130:131]
	s_addc_u32 s5, s31, s13
	s_add_i32 s41, s41, s0
	global_load_lds_dwordx4 v[206:207], off
	v_lshl_add_u64 v[206:207], s[4:5], 0, v[128:129]
	s_mov_b32 m0, s41
	s_nop 0
	global_load_lds_dwordx4 v[206:207], off
	v_lshl_add_u64 v[206:207], s[4:5], 0, v[130:131]
	s_add_i32 m0, s41, 0x2000
	s_nop 0
	global_load_lds_dwordx4 v[206:207], off
	v_lshl_add_u64 v[206:207], s[34:35], 0, v[128:129]
	s_mov_b32 m0, s11
	s_nop 0
	global_load_lds_dwordx4 v[206:207], off
	v_lshl_add_u64 v[206:207], s[34:35], 0, v[130:131]
	s_mov_b32 m0, s48
	s_nop 0
	global_load_lds_dwordx4 v[206:207], off
	s_waitcnt vmcnt(8)
	s_waitcnt lgkmcnt(0)
	s_barrier
; #define PG8_STAGE(bufoff, gbase, voff) do { _Pragma("unroll") for (int _i = 0; _i < 2; ++_i) \
;         __builtin_amdgcn_global_load_lds((const unsigned*)((const char*)(gbase) + (voff)[_i]), (PG8_LAS unsigned*)(lds + (bufoff) + ldsw + _i * 8192), 16, 0, 0); } while (0)
; #define PG8_LDA(dst, b, h) do { _Pragma("unroll") for (int m = 0; m < 4; ++m) _Pragma("unroll") for (int k = 0; k < 2; ++k) dst[m][k] = *(const PG8_LAS bf16x8*)(lds + PG8_SA(b, h) + aoff + m * 2048 + k * 1024); } while (0)
; #define PG8_LDB(dst, b, h) do { _Pragma("unroll") for (int n = 0; n < 2; ++n) _Pragma("unroll") for (int k = 0; k < 2; ++k) dst[n][k] = *(const PG8_LAS bf16x8*)(lds + PG8_SB(b, h) + boff + n * 2048 + k * 1024); } while (0)
; #define PG8_MMA(ai, bj, At, Bt) do { __builtin_amdgcn_s_setprio(1); _Pragma("unroll") for (int m = 0; m < 4; ++m) _Pragma("unroll") for (int n = 0; n < 2; ++n) _Pragma("unroll") for (int k = 0; k < 2; ++k) \
;         acc[ai][bj][m][n] = __builtin_amdgcn_mfma_f32_16x16x32_bf16(Bt[n][k], At[m][k], acc[ai][bj][m][n], 0, 0, 0); __builtin_amdgcn_s_setprio(0); } while (0)
; #define PG8_WAIT_V(n) asm volatile("s_waitcnt vmcnt(" #n ")" ::: "memory")
; #define PG8_WAIT_L(n) asm volatile("s_waitcnt lgkmcnt(" #n ")" ::: "memory")
; #define PG8_BAR __builtin_amdgcn_s_barrier()
; #define PG8_SCHED __builtin_amdgcn_sched_barrier(0)
; template <class Epi, class Sched, bool ALIGN_EPI = false, bool SP2 = false>
; __device__ __forceinline__ void gemm_phase(PG8_LAS unsigned char* lds, const Gemm g, const Sched& S, const Epi& E, const int tid_in) {
;     ...
;             PG8_WAIT_V(8); PG8_WAIT_L(0); PG8_BAR; PG8_MMA(1, 0, At, B0); PG8_MMA(1, 1, At, B1); PG8_BAR; PG8_SCHED;
;             PG8_LDB(B0, 1, 0); PG8_LDB(B1, 1, 1); PG8_SCHED; PG8_LDA(At, 1, 0); PG8_STAGE(PG8_SA(0, 1), a2 + hstepA, voffA);
;             PG8_WAIT_V(8); PG8_WAIT_L(0); PG8_BAR; PG8_MMA(0, 0, At, B0); PG8_MMA(0, 1, At, B1); PG8_BAR; PG8_SCHED;
	s_setprio 1
	s_waitcnt lgkmcnt(0)
	v_mfma_f32_16x16x32_bf16 v[60:63], v[140:143], v[172:175], 0
	v_mfma_f32_16x16x32_bf16 v[56:59], v[148:151], v[172:175], 0
	v_mfma_f32_16x16x32_bf16 v[44:47], v[140:143], v[180:183], 0
	v_mfma_f32_16x16x32_bf16 v[40:43], v[148:151], v[180:183], 0
	v_mfma_f32_16x16x32_bf16 v[28:31], v[140:143], v[190:193], 0
	v_mfma_f32_16x16x32_bf16 v[24:27], v[148:151], v[190:193], 0
	v_mfma_f32_16x16x32_bf16 v[12:15], v[140:143], v[198:201], 0
	v_mfma_f32_16x16x32_bf16 v[8:11], v[148:151], v[198:201], 0
	v_mfma_f32_16x16x32_bf16 v[60:63], v[144:147], v[176:179], v[60:63]
	v_mfma_f32_16x16x32_bf16 v[56:59], v[152:155], v[176:179], v[56:59]
	v_mfma_f32_16x16x32_bf16 v[44:47], v[144:147], v[184:187], v[44:47]
	v_mfma_f32_16x16x32_bf16 v[40:43], v[152:155], v[184:187], v[40:43]
	v_mfma_f32_16x16x32_bf16 v[28:31], v[144:147], v[194:197], v[28:31]
	v_mfma_f32_16x16x32_bf16 v[24:27], v[152:155], v[194:197], v[24:27]
	v_mfma_f32_16x16x32_bf16 v[12:15], v[144:147], v[202:205], v[12:15]
	v_mfma_f32_16x16x32_bf16 v[8:11], v[152:155], v[202:205], v[8:11]
	s_setprio 0
	s_setprio 1
	v_mfma_f32_16x16x32_bf16 v[52:55], v[156:159], v[172:175], 0
	v_mfma_f32_16x16x32_bf16 v[48:51], v[164:167], v[172:175], 0
	v_mfma_f32_16x16x32_bf16 v[36:39], v[156:159], v[180:183], 0
	v_mfma_f32_16x16x32_bf16 v[32:35], v[164:167], v[180:183], 0
	v_mfma_f32_16x16x32_bf16 v[20:23], v[156:159], v[190:193], 0
	v_mfma_f32_16x16x32_bf16 v[16:19], v[164:167], v[190:193], 0
	v_mfma_f32_16x16x32_bf16 v[4:7], v[156:159], v[198:201], 0
	v_mfma_f32_16x16x32_bf16 v[0:3], v[164:167], v[198:201], 0
	v_mfma_f32_16x16x32_bf16 v[52:55], v[160:163], v[176:179], v[52:55]
	v_mfma_f32_16x16x32_bf16 v[48:51], v[168:171], v[176:179], v[48:51]
	v_mfma_f32_16x16x32_bf16 v[36:39], v[160:163], v[184:187], v[36:39]
	v_mfma_f32_16x16x32_bf16 v[32:35], v[168:171], v[184:187], v[32:35]
	v_mfma_f32_16x16x32_bf16 v[20:23], v[160:163], v[194:197], v[20:23]
	v_mfma_f32_16x16x32_bf16 v[16:19], v[168:171], v[194:197], v[16:19]
	v_mfma_f32_16x16x32_bf16 v[4:7], v[160:163], v[202:205], v[4:7]
	v_mfma_f32_16x16x32_bf16 v[0:3], v[168:171], v[202:205], v[0:3]
	s_setprio 0
	s_barrier
	s_add_i32 s41, 0, 0x18000
	s_add_i32 s71, 0, 0x1c000
	v_add_u32_e32 v152, s41, v138
	v_add_u32_e32 v168, s71, v138
	ds_read_b128 v[140:143], v152
	ds_read_b128 v[144:147], v152 offset:1024
	ds_read_b128 v[148:151], v152 offset:2048
	ds_read_b128 v[152:155], v152 offset:3072
	ds_read_b128 v[156:159], v168
	ds_read_b128 v[160:163], v168 offset:1024
	ds_read_b128 v[164:167], v168 offset:2048
	ds_read_b128 v[168:171], v168 offset:3072
	s_add_u32 s4, s34, s12
	s_addc_u32 s5, s35, s13
	s_mov_b32 m0, s49
	v_lshl_add_u64 v[206:207], s[4:5], 0, v[128:129]
	ds_read_b128 v[172:175], v139 offset:32768
	ds_read_b128 v[176:179], v139 offset:33792
	ds_read_b128 v[180:183], v139 offset:34816
	ds_read_b128 v[184:187], v139 offset:35840
	ds_read_b128 v[190:193], v139 offset:36864
	ds_read_b128 v[194:197], v139 offset:37888
	ds_read_b128 v[198:201], v139 offset:38912
	ds_read_b128 v[202:205], v139 offset:39936
	global_load_lds_dwordx4 v[206:207], off
	v_lshl_add_u64 v[206:207], s[4:5], 0, v[130:131]
	s_mov_b32 m0, s50
	s_nop 0
	global_load_lds_dwordx4 v[206:207], off
	s_waitcnt vmcnt(8)
	s_waitcnt lgkmcnt(0)
	s_barrier
	s_setprio 1
	s_waitcnt lgkmcnt(0)
	v_mfma_f32_16x16x32_bf16 v[120:123], v[140:143], v[172:175], v[120:123]
	v_mfma_f32_16x16x32_bf16 v[124:127], v[148:151], v[172:175], v[124:127]
	v_mfma_f32_16x16x32_bf16 v[108:111], v[140:143], v[180:183], v[108:111]
	v_mfma_f32_16x16x32_bf16 v[104:107], v[148:151], v[180:183], v[104:107]
	v_mfma_f32_16x16x32_bf16 v[92:95], v[140:143], v[190:193], v[92:95]
	v_mfma_f32_16x16x32_bf16 v[88:91], v[148:151], v[190:193], v[88:91]
	v_mfma_f32_16x16x32_bf16 v[76:79], v[140:143], v[198:201], v[76:79]
	v_mfma_f32_16x16x32_bf16 v[72:75], v[148:151], v[198:201], v[72:75]
	v_mfma_f32_16x16x32_bf16 v[120:123], v[144:147], v[176:179], v[120:123]
	v_mfma_f32_16x16x32_bf16 v[124:127], v[152:155], v[176:179], v[124:127]
	v_mfma_f32_16x16x32_bf16 v[108:111], v[144:147], v[184:187], v[108:111]
	v_mfma_f32_16x16x32_bf16 v[104:107], v[152:155], v[184:187], v[104:107]
	v_mfma_f32_16x16x32_bf16 v[92:95], v[144:147], v[194:197], v[92:95]
	v_mfma_f32_16x16x32_bf16 v[88:91], v[152:155], v[194:197], v[88:91]
	v_mfma_f32_16x16x32_bf16 v[76:79], v[144:147], v[202:205], v[76:79]
	v_mfma_f32_16x16x32_bf16 v[72:75], v[152:155], v[202:205], v[72:75]
	s_setprio 0
	s_setprio 1
	v_mfma_f32_16x16x32_bf16 v[116:119], v[156:159], v[172:175], v[116:119]
	v_mfma_f32_16x16x32_bf16 v[112:115], v[164:167], v[172:175], v[112:115]
	v_mfma_f32_16x16x32_bf16 v[100:103], v[156:159], v[180:183], v[100:103]
	v_mfma_f32_16x16x32_bf16 v[96:99], v[164:167], v[180:183], v[96:99]
	v_mfma_f32_16x16x32_bf16 v[84:87], v[156:159], v[190:193], v[84:87]
	v_mfma_f32_16x16x32_bf16 v[80:83], v[164:167], v[190:193], v[80:83]
	v_mfma_f32_16x16x32_bf16 v[68:71], v[156:159], v[198:201], v[68:71]
	v_mfma_f32_16x16x32_bf16 v[64:67], v[164:167], v[198:201], v[64:67]
	v_mfma_f32_16x16x32_bf16 v[116:119], v[160:163], v[176:179], v[116:119]
	v_mfma_f32_16x16x32_bf16 v[112:115], v[168:171], v[176:179], v[112:115]
	v_mfma_f32_16x16x32_bf16 v[100:103], v[160:163], v[184:187], v[100:103]
	v_mfma_f32_16x16x32_bf16 v[96:99], v[168:171], v[184:187], v[96:99]
	v_mfma_f32_16x16x32_bf16 v[84:87], v[160:163], v[194:197], v[84:87]
	v_mfma_f32_16x16x32_bf16 v[80:83], v[168:171], v[194:197], v[80:83]
	v_mfma_f32_16x16x32_bf16 v[68:71], v[160:163], v[202:205], v[68:71]
	v_mfma_f32_16x16x32_bf16 v[64:67], v[168:171], v[202:205], v[64:67]
	s_setprio 0
	s_barrier
; #define PG8_STAGE(bufoff, gbase, voff) do { _Pragma("unroll") for (int _i = 0; _i < 2; ++_i) \
;         __builtin_amdgcn_global_load_lds((const unsigned*)((const char*)(gbase) + (voff)[_i]), (PG8_LAS unsigned*)(lds + (bufoff) + ldsw + _i * 8192), 16, 0, 0); } while (0)
; #define PG8_LDA(dst, b, h) do { _Pragma("unroll") for (int m = 0; m < 4; ++m) _Pragma("unroll") for (int k = 0; k < 2; ++k) dst[m][k] = *(const PG8_LAS bf16x8*)(lds + PG8_SA(b, h) + aoff + m * 2048 + k * 1024); } while (0)
; #define PG8_MMA(ai, bj, At, Bt) do { __builtin_amdgcn_s_setprio(1); _Pragma("unroll") for (int m = 0; m < 4; ++m) _Pragma("unroll") for (int n = 0; n < 2; ++n) _Pragma("unroll") for (int k = 0; k < 2; ++k) \
;         acc[ai][bj][m][n] = __builtin_amdgcn_mfma_f32_16x16x32_bf16(Bt[n][k], At[m][k], acc[ai][bj][m][n], 0, 0, 0); __builtin_amdgcn_s_setprio(0); } while (0)
; #define PG8_WAIT_V(n) asm volatile("s_waitcnt vmcnt(" #n ")" ::: "memory")
; #define PG8_WAIT_L(n) asm volatile("s_waitcnt lgkmcnt(" #n ")" ::: "memory")
; #define PG8_BAR __builtin_amdgcn_s_barrier()
; #define PG8_SCHED __builtin_amdgcn_sched_barrier(0)
; template <class Epi, class Sched, bool ALIGN_EPI = false, bool SP2 = false>
; __device__ __forceinline__ void gemm_phase(PG8_LAS unsigned char* lds, const Gemm g, const Sched& S, const Epi& E, const int tid_in) {
;     ...
;         for (int t = 0; t < nt; t += 2) {
;             const bool last = (t == nt - 2);
;             const char* a1 = cA + (size_t)(t + 1) * kstepA;
;             const char* a2 = last ? nA : cA + (size_t)(t + 2) * kstepA; const char* b2 = last ? nB : cB + (size_t)(t + 2) * kstepB;
;             const char* a3 = a2 + kstepA; const char* b3 = b2 + kstepB;
;     ...
;             PG8_LDA(At, 1, 1); PG8_STAGE(PG8_SB(1, 0), b3, voffB); PG8_STAGE(PG8_SB(1, 1), b3 + hstepB, voffB); PG8_STAGE(PG8_SA(1, 0), a3, voffA);
;             PG8_WAIT_V(8); PG8_WAIT_L(0); PG8_BAR; PG8_MMA(1, 0, At, B0); PG8_MMA(1, 1, At, B1); PG8_BAR; PG8_SCHED;
	s_add_u32 s4, s30, 0x4000
	s_addc_u32 s5, s31, 0
	s_add_i32 s30, s41, s0
	v_lshl_add_u64 v[206:207], s[4:5], 0, v[128:129]
	s_mov_b32 m0, s30
	ds_read_b128 v[172:175], v139 offset:49152
	ds_read_b128 v[176:179], v139 offset:50176
	ds_read_b128 v[180:183], v139 offset:51200
	ds_read_b128 v[184:187], v139 offset:52224
	ds_read_b128 v[190:193], v139 offset:53248
	ds_read_b128 v[194:197], v139 offset:54272
	ds_read_b128 v[198:201], v139 offset:55296
	ds_read_b128 v[202:205], v139 offset:56320
	global_load_lds_dwordx4 v[206:207], off
	s_add_i32 m0, s30, 0x2000
	v_lshl_add_u64 v[206:207], s[4:5], 0, v[130:131]
	s_add_u32 s4, s4, s12
	s_addc_u32 s5, s5, s13
	s_add_i32 s30, s71, s0
	global_load_lds_dwordx4 v[206:207], off
	v_lshl_add_u64 v[206:207], s[4:5], 0, v[128:129]
	s_mov_b32 m0, s30
	s_nop 0
	global_load_lds_dwordx4 v[206:207], off
	v_lshl_add_u64 v[206:207], s[4:5], 0, v[130:131]
	s_add_i32 m0, s30, 0x2000
	s_nop 0
	global_load_lds_dwordx4 v[206:207], off
	v_lshl_add_u64 v[206:207], s[28:29], 0, v[128:129]
	s_mov_b32 m0, s56
	s_nop 0
	global_load_lds_dwordx4 v[206:207], off
	v_lshl_add_u64 v[206:207], s[28:29], 0, v[130:131]
	s_mov_b32 m0, s57
	s_nop 0
	global_load_lds_dwordx4 v[206:207], off
	s_waitcnt vmcnt(8)
	s_waitcnt lgkmcnt(0)
	s_barrier
	s_setprio 1
	s_waitcnt lgkmcnt(0)
	v_mfma_f32_16x16x32_bf16 v[60:63], v[140:143], v[172:175], v[60:63]
	v_mfma_f32_16x16x32_bf16 v[56:59], v[148:151], v[172:175], v[56:59]
	v_mfma_f32_16x16x32_bf16 v[44:47], v[140:143], v[180:183], v[44:47]
	v_mfma_f32_16x16x32_bf16 v[40:43], v[148:151], v[180:183], v[40:43]
	v_mfma_f32_16x16x32_bf16 v[28:31], v[140:143], v[190:193], v[28:31]
	v_mfma_f32_16x16x32_bf16 v[24:27], v[148:151], v[190:193], v[24:27]
	v_mfma_f32_16x16x32_bf16 v[12:15], v[140:143], v[198:201], v[12:15]
	v_mfma_f32_16x16x32_bf16 v[8:11], v[148:151], v[198:201], v[8:11]
	v_mfma_f32_16x16x32_bf16 v[60:63], v[144:147], v[176:179], v[60:63]
	v_mfma_f32_16x16x32_bf16 v[56:59], v[152:155], v[176:179], v[56:59]
	v_mfma_f32_16x16x32_bf16 v[44:47], v[144:147], v[184:187], v[44:47]
	v_mfma_f32_16x16x32_bf16 v[40:43], v[152:155], v[184:187], v[40:43]
	v_mfma_f32_16x16x32_bf16 v[28:31], v[144:147], v[194:197], v[28:31]
	v_mfma_f32_16x16x32_bf16 v[24:27], v[152:155], v[194:197], v[24:27]
	v_mfma_f32_16x16x32_bf16 v[12:15], v[144:147], v[202:205], v[12:15]
	v_mfma_f32_16x16x32_bf16 v[8:11], v[152:155], v[202:205], v[8:11]
	s_setprio 0
	s_setprio 1
	v_mfma_f32_16x16x32_bf16 v[52:55], v[156:159], v[172:175], v[52:55]
	v_mfma_f32_16x16x32_bf16 v[48:51], v[164:167], v[172:175], v[48:51]
	v_mfma_f32_16x16x32_bf16 v[36:39], v[156:159], v[180:183], v[36:39]
	v_mfma_f32_16x16x32_bf16 v[32:35], v[164:167], v[180:183], v[32:35]
	v_mfma_f32_16x16x32_bf16 v[20:23], v[156:159], v[190:193], v[20:23]
	v_mfma_f32_16x16x32_bf16 v[16:19], v[164:167], v[190:193], v[16:19]
	v_mfma_f32_16x16x32_bf16 v[4:7], v[156:159], v[198:201], v[4:7]
	v_mfma_f32_16x16x32_bf16 v[0:3], v[164:167], v[198:201], v[0:3]
	v_mfma_f32_16x16x32_bf16 v[52:55], v[160:163], v[176:179], v[52:55]
	v_mfma_f32_16x16x32_bf16 v[48:51], v[168:171], v[176:179], v[48:51]
	v_mfma_f32_16x16x32_bf16 v[36:39], v[160:163], v[184:187], v[36:39]
	v_mfma_f32_16x16x32_bf16 v[32:35], v[168:171], v[184:187], v[32:35]
	v_mfma_f32_16x16x32_bf16 v[20:23], v[160:163], v[194:197], v[20:23]
	v_mfma_f32_16x16x32_bf16 v[16:19], v[168:171], v[194:197], v[16:19]
	v_mfma_f32_16x16x32_bf16 v[4:7], v[160:163], v[202:205], v[4:7]
	v_mfma_f32_16x16x32_bf16 v[0:3], v[168:171], v[202:205], v[0:3]
	s_setprio 0
	s_barrier
	s_add_u32 s26, s26, 0x8000
	s_addc_u32 s27, s27, 0
	s_add_u32 s6, s6, 0x8000
	s_addc_u32 s7, s7, 0
	s_cmp_ge_i32 s40, s10
	s_mov_b32 s28, s40
	s_cbranch_scc1 .LBB0_121
	.p2align	6

; #define PG8_STAGE(bufoff, gbase, voff) do { _Pragma("unroll") for (int _i = 0; _i < 2; ++_i) \
;         __builtin_amdgcn_global_load_lds((const unsigned*)((const char*)(gbase) + (voff)[_i]), (PG8_LAS unsigned*)(lds + (bufoff) + ldsw + _i * 8192), 16, 0, 0); } while (0)
; #define PG8_LDA(dst, b, h) do { _Pragma("unroll") for (int m = 0; m < 4; ++m) _Pragma("unroll") for (int k = 0; k < 2; ++k) dst[m][k] = *(const PG8_LAS bf16x8*)(lds + PG8_SA(b, h) + aoff + m * 2048 + k * 1024); } while (0)
; #define PG8_LDB(dst, b, h) do { _Pragma("unroll") for (int n = 0; n < 2; ++n) _Pragma("unroll") for (int k = 0; k < 2; ++k) dst[n][k] = *(const PG8_LAS bf16x8*)(lds + PG8_SB(b, h) + boff + n * 2048 + k * 1024); } while (0)
; #define PG8_MMA(ai, bj, At, Bt) do { __builtin_amdgcn_s_setprio(1); _Pragma("unroll") for (int m = 0; m < 4; ++m) _Pragma("unroll") for (int n = 0; n < 2; ++n) _Pragma("unroll") for (int k = 0; k < 2; ++k) \
;         acc[ai][bj][m][n] = __builtin_amdgcn_mfma_f32_16x16x32_bf16(Bt[n][k], At[m][k], acc[ai][bj][m][n], 0, 0, 0); __builtin_amdgcn_s_setprio(0); } while (0)
; #define PG8_WAIT_V(n) asm volatile("s_waitcnt vmcnt(" #n ")" ::: "memory")
; #define PG8_WAIT_L(n) asm volatile("s_waitcnt lgkmcnt(" #n ")" ::: "memory")
; template <class Epi, class Sched, bool ALIGN_EPI = false, bool SP2 = false>
; __device__ __forceinline__ void gemm_phase(PG8_LAS unsigned char* lds, const Gemm g, const Sched& S, const Epi& E, const int tid_in) {
;     ...
;             const bool last = (t == nt - 2);
;             const char* a1 = cA + (size_t)(t + 1) * kstepA;
;             const char* a2 = last ? nA : cA + (size_t)(t + 2) * kstepA; const char* b2 = last ? nB : cB + (size_t)(t + 2) * kstepB;
;             const char* a3 = a2 + kstepA; const char* b3 = b2 + kstepB;
;             if (last && has_next) S.a_ready(nxt);
;             if constexpr (SP2) {
;             PG8_LDB(B0, 0, 0); PG8_LDB(B1, 0, 1); PG8_SCHED; PG8_LDA(At, 0, 0); PG8_STAGE(PG8_SA(1, 1), a1 + hstepA, voffA);
;             PG8_WAIT_V(8); PG8_WAIT_L(0); PG8_BAR; PG8_MMA(0, 0, At, B0); PG8_MMA(0, 1, At, B1); PG8_BAR; PG8_SCHED;
;             PG8_LDA(At, 0, 1); PG8_STAGE(PG8_SB(0, 0), b2, voffB); PG8_STAGE(PG8_SB(0, 1), b2 + hstepB, voffB); PG8_STAGE(PG8_SA(0, 0), a2, voffA);
;             PG8_WAIT_V(8); PG8_WAIT_L(0); PG8_BAR; PG8_MMA(1, 0, At, B0); PG8_MMA(1, 1, At, B1); PG8_BAR; PG8_SCHED;
.LBB0_143:
	s_andn2_b64 vcc, exec, s[18:19]
	s_cbranch_vccnz .Lzero_acc_2
	s_add_u32 s26, s26, 0x4000
	s_addc_u32 s27, s27, 0
	s_add_u32 s6, s28, 0x8000
	s_addc_u32 s7, s29, 0
	s_mov_b32 s28, 0
	s_add_i32 s40, s28, 2
	s_add_u32 s4, s26, 0x4000
	s_addc_u32 s5, s27, 0
	s_cmp_eq_u32 s43, s28
	s_cselect_b32 s34, s22, s4
	s_cselect_b32 s35, s23, s5
	s_cselect_b32 s30, s24, s6
	s_cselect_b32 s31, s25, s7
	s_add_u32 s28, s34, 0x4000
	s_addc_u32 s29, s35, 0
	s_add_i32 s4, 0, 0x10000
	s_add_i32 s41, 0, 0x14000
	v_add_u32_e32 v140, s4, v190
	v_add_u32_e32 v166, s41, v190
	ds_read_b128 v[128:131], v140
	ds_read_b128 v[132:135], v140 offset:1024
	ds_read_b128 v[136:139], v140 offset:2048
	ds_read_b128 v[140:143], v140 offset:3072
	ds_read_b128 v[144:147], v166
	ds_read_b128 v[148:151], v166 offset:1024
	ds_read_b128 v[152:155], v166 offset:2048
	ds_read_b128 v[166:169], v166 offset:3072
	v_lshl_add_u64 v[186:187], s[26:27], 0, v[162:163]
	s_add_i32 m0, s1, 0xc000
	ds_read_b128 v[170:173], v194
	ds_read_b128 v[174:177], v194 offset:1024
	ds_read_b128 v[178:181], v194 offset:2048
	ds_read_b128 v[182:185], v194 offset:3072
	ds_read_b128 v[196:199], v194 offset:4096
	ds_read_b128 v[200:203], v194 offset:5120
	ds_read_b128 v[204:207], v194 offset:6144
	ds_read_b128 v[210:213], v194 offset:7168
	global_load_lds_dwordx4 v[186:187], off
	v_lshl_add_u64 v[186:187], s[26:27], 0, v[164:165]
	s_add_i32 m0, s1, 0xe000
	s_nop 0
	global_load_lds_dwordx4 v[186:187], off
	s_waitcnt vmcnt(8)
	s_waitcnt lgkmcnt(0)
	s_barrier
	s_setprio 1
	s_waitcnt lgkmcnt(0)
	v_mfma_f32_16x16x32_bf16 v[124:127], v[128:131], v[170:173], 0
	v_mfma_f32_16x16x32_bf16 v[120:123], v[136:139], v[170:173], 0
	v_mfma_f32_16x16x32_bf16 v[108:111], v[128:131], v[178:181], 0
	v_mfma_f32_16x16x32_bf16 v[104:107], v[136:139], v[178:181], 0
	v_mfma_f32_16x16x32_bf16 v[92:95], v[128:131], v[196:199], 0
	v_mfma_f32_16x16x32_bf16 v[88:91], v[136:139], v[196:199], 0
	v_mfma_f32_16x16x32_bf16 v[76:79], v[128:131], v[204:207], 0
	v_mfma_f32_16x16x32_bf16 v[72:75], v[136:139], v[204:207], 0
	v_mfma_f32_16x16x32_bf16 v[124:127], v[132:135], v[174:177], v[124:127]
	v_mfma_f32_16x16x32_bf16 v[120:123], v[140:143], v[174:177], v[120:123]
	v_mfma_f32_16x16x32_bf16 v[108:111], v[132:135], v[182:185], v[108:111]
	v_mfma_f32_16x16x32_bf16 v[104:107], v[140:143], v[182:185], v[104:107]
	v_mfma_f32_16x16x32_bf16 v[92:95], v[132:135], v[200:203], v[92:95]
	v_mfma_f32_16x16x32_bf16 v[88:91], v[140:143], v[200:203], v[88:91]
	v_mfma_f32_16x16x32_bf16 v[76:79], v[132:135], v[210:213], v[76:79]
	v_mfma_f32_16x16x32_bf16 v[72:75], v[140:143], v[210:213], v[72:75]
	s_setprio 0
	s_setprio 1
	v_mfma_f32_16x16x32_bf16 v[116:119], v[144:147], v[170:173], 0
	v_mfma_f32_16x16x32_bf16 v[112:115], v[152:155], v[170:173], 0
	v_mfma_f32_16x16x32_bf16 v[100:103], v[144:147], v[178:181], 0
	v_mfma_f32_16x16x32_bf16 v[96:99], v[152:155], v[178:181], 0
	v_mfma_f32_16x16x32_bf16 v[84:87], v[144:147], v[196:199], 0
	v_mfma_f32_16x16x32_bf16 v[80:83], v[152:155], v[196:199], 0
	v_mfma_f32_16x16x32_bf16 v[68:71], v[144:147], v[204:207], 0
	v_mfma_f32_16x16x32_bf16 v[64:67], v[152:155], v[204:207], 0
	v_mfma_f32_16x16x32_bf16 v[116:119], v[148:151], v[174:177], v[116:119]
	v_mfma_f32_16x16x32_bf16 v[112:115], v[166:169], v[174:177], v[112:115]
	v_mfma_f32_16x16x32_bf16 v[100:103], v[148:151], v[182:185], v[100:103]
	v_mfma_f32_16x16x32_bf16 v[96:99], v[166:169], v[182:185], v[96:99]
	v_mfma_f32_16x16x32_bf16 v[84:87], v[148:151], v[200:203], v[84:87]
	v_mfma_f32_16x16x32_bf16 v[80:83], v[166:169], v[200:203], v[80:83]
	v_mfma_f32_16x16x32_bf16 v[68:71], v[148:151], v[210:213], v[68:71]
	v_mfma_f32_16x16x32_bf16 v[64:67], v[166:169], v[210:213], v[64:67]
	s_setprio 0
	s_barrier
	s_add_i32 s4, s4, s0
	v_lshl_add_u64 v[186:187], s[30:31], 0, v[156:157]
	s_mov_b32 m0, s4
	ds_read_b128 v[170:173], v194 offset:16384
	ds_read_b128 v[174:177], v194 offset:17408
	ds_read_b128 v[178:181], v194 offset:18432
	ds_read_b128 v[182:185], v194 offset:19456
	ds_read_b128 v[196:199], v194 offset:20480
	ds_read_b128 v[200:203], v194 offset:21504
	ds_read_b128 v[204:207], v194 offset:22528
	ds_read_b128 v[210:213], v194 offset:23552
	global_load_lds_dwordx4 v[186:187], off
	s_add_i32 m0, s4, 0x2000
	s_add_u32 s4, s30, s12
	v_lshl_add_u64 v[186:187], s[30:31], 0, v[158:159]
	s_addc_u32 s5, s31, s13
	s_add_i32 s41, s41, s0
	global_load_lds_dwordx4 v[186:187], off
	v_lshl_add_u64 v[186:187], s[4:5], 0, v[156:157]
	s_mov_b32 m0, s41
	s_nop 0
	global_load_lds_dwordx4 v[186:187], off
	v_lshl_add_u64 v[186:187], s[4:5], 0, v[158:159]
	s_add_i32 m0, s41, 0x2000
	s_nop 0
	global_load_lds_dwordx4 v[186:187], off
	v_lshl_add_u64 v[186:187], s[34:35], 0, v[156:157]
	s_mov_b32 m0, s1
	s_nop 0
	global_load_lds_dwordx4 v[186:187], off
	v_lshl_add_u64 v[186:187], s[34:35], 0, v[158:159]
	s_mov_b32 m0, s3
	s_nop 0
	global_load_lds_dwordx4 v[186:187], off
	s_waitcnt vmcnt(8)
	s_waitcnt lgkmcnt(0)
	s_barrier
; #define PG8_STAGE(bufoff, gbase, voff) do { _Pragma("unroll") for (int _i = 0; _i < 2; ++_i) \
;         __builtin_amdgcn_global_load_lds((const unsigned*)((const char*)(gbase) + (voff)[_i]), (PG8_LAS unsigned*)(lds + (bufoff) + ldsw + _i * 8192), 16, 0, 0); } while (0)
; #define PG8_LDA(dst, b, h) do { _Pragma("unroll") for (int m = 0; m < 4; ++m) _Pragma("unroll") for (int k = 0; k < 2; ++k) dst[m][k] = *(const PG8_LAS bf16x8*)(lds + PG8_SA(b, h) + aoff + m * 2048 + k * 1024); } while (0)
; #define PG8_LDB(dst, b, h) do { _Pragma("unroll") for (int n = 0; n < 2; ++n) _Pragma("unroll") for (int k = 0; k < 2; ++k) dst[n][k] = *(const PG8_LAS bf16x8*)(lds + PG8_SB(b, h) + boff + n * 2048 + k * 1024); } while (0)
; #define PG8_MMA(ai, bj, At, Bt) do { __builtin_amdgcn_s_setprio(1); _Pragma("unroll") for (int m = 0; m < 4; ++m) _Pragma("unroll") for (int n = 0; n < 2; ++n) _Pragma("unroll") for (int k = 0; k < 2; ++k) \
;         acc[ai][bj][m][n] = __builtin_amdgcn_mfma_f32_16x16x32_bf16(Bt[n][k], At[m][k], acc[ai][bj][m][n], 0, 0, 0); __builtin_amdgcn_s_setprio(0); } while (0)
; #define PG8_WAIT_V(n) asm volatile("s_waitcnt vmcnt(" #n ")" ::: "memory")
; #define PG8_WAIT_L(n) asm volatile("s_waitcnt lgkmcnt(" #n ")" ::: "memory")
; #define PG8_BAR __builtin_amdgcn_s_barrier()
; #define PG8_SCHED __builtin_amdgcn_sched_barrier(0)
; template <class Epi, class Sched, bool ALIGN_EPI = false, bool SP2 = false>
; __device__ __forceinline__ void gemm_phase(PG8_LAS unsigned char* lds, const Gemm g, const Sched& S, const Epi& E, const int tid_in) {
;     ...
;             PG8_WAIT_V(8); PG8_WAIT_L(0); PG8_BAR; PG8_MMA(1, 0, At, B0); PG8_MMA(1, 1, At, B1); PG8_BAR; PG8_SCHED;
;             PG8_LDB(B0, 1, 0); PG8_LDB(B1, 1, 1); PG8_SCHED; PG8_LDA(At, 1, 0); PG8_STAGE(PG8_SA(0, 1), a2 + hstepA, voffA);
;             PG8_WAIT_V(8); PG8_WAIT_L(0); PG8_BAR; PG8_MMA(0, 0, At, B0); PG8_MMA(0, 1, At, B1); PG8_BAR; PG8_SCHED;
	s_setprio 1
	s_waitcnt lgkmcnt(0)
	v_mfma_f32_16x16x32_bf16 v[60:63], v[128:131], v[170:173], 0
	v_mfma_f32_16x16x32_bf16 v[56:59], v[136:139], v[170:173], 0
	v_mfma_f32_16x16x32_bf16 v[44:47], v[128:131], v[178:181], 0
	v_mfma_f32_16x16x32_bf16 v[40:43], v[136:139], v[178:181], 0
	v_mfma_f32_16x16x32_bf16 v[28:31], v[128:131], v[196:199], 0
	v_mfma_f32_16x16x32_bf16 v[24:27], v[136:139], v[196:199], 0
	v_mfma_f32_16x16x32_bf16 v[12:15], v[128:131], v[204:207], 0
	v_mfma_f32_16x16x32_bf16 v[8:11], v[136:139], v[204:207], 0
	v_mfma_f32_16x16x32_bf16 v[60:63], v[132:135], v[174:177], v[60:63]
	v_mfma_f32_16x16x32_bf16 v[56:59], v[140:143], v[174:177], v[56:59]
	v_mfma_f32_16x16x32_bf16 v[44:47], v[132:135], v[182:185], v[44:47]
	v_mfma_f32_16x16x32_bf16 v[40:43], v[140:143], v[182:185], v[40:43]
	v_mfma_f32_16x16x32_bf16 v[28:31], v[132:135], v[200:203], v[28:31]
	v_mfma_f32_16x16x32_bf16 v[24:27], v[140:143], v[200:203], v[24:27]
	v_mfma_f32_16x16x32_bf16 v[12:15], v[132:135], v[210:213], v[12:15]
	v_mfma_f32_16x16x32_bf16 v[8:11], v[140:143], v[210:213], v[8:11]
	s_setprio 0
	s_setprio 1
	v_mfma_f32_16x16x32_bf16 v[52:55], v[144:147], v[170:173], 0
	v_mfma_f32_16x16x32_bf16 v[48:51], v[152:155], v[170:173], 0
	v_mfma_f32_16x16x32_bf16 v[36:39], v[144:147], v[178:181], 0
	v_mfma_f32_16x16x32_bf16 v[32:35], v[152:155], v[178:181], 0
	v_mfma_f32_16x16x32_bf16 v[20:23], v[144:147], v[196:199], 0
	v_mfma_f32_16x16x32_bf16 v[16:19], v[152:155], v[196:199], 0
	v_mfma_f32_16x16x32_bf16 v[4:7], v[144:147], v[204:207], 0
	v_mfma_f32_16x16x32_bf16 v[0:3], v[152:155], v[204:207], 0
	v_mfma_f32_16x16x32_bf16 v[52:55], v[148:151], v[174:177], v[52:55]
	v_mfma_f32_16x16x32_bf16 v[48:51], v[166:169], v[174:177], v[48:51]
	v_mfma_f32_16x16x32_bf16 v[36:39], v[148:151], v[182:185], v[36:39]
	v_mfma_f32_16x16x32_bf16 v[32:35], v[166:169], v[182:185], v[32:35]
	v_mfma_f32_16x16x32_bf16 v[20:23], v[148:151], v[200:203], v[20:23]
	v_mfma_f32_16x16x32_bf16 v[16:19], v[166:169], v[200:203], v[16:19]
	v_mfma_f32_16x16x32_bf16 v[4:7], v[148:151], v[210:213], v[4:7]
	v_mfma_f32_16x16x32_bf16 v[0:3], v[166:169], v[210:213], v[0:3]
	s_setprio 0
	s_barrier
	s_add_i32 s41, 0, 0x18000
	s_add_i32 s64, 0, 0x1c000
	v_add_u32_e32 v140, s41, v190
	v_add_u32_e32 v166, s64, v190
	ds_read_b128 v[128:131], v140
	ds_read_b128 v[132:135], v140 offset:1024
	ds_read_b128 v[136:139], v140 offset:2048
	ds_read_b128 v[140:143], v140 offset:3072
	ds_read_b128 v[144:147], v166
	ds_read_b128 v[148:151], v166 offset:1024
	ds_read_b128 v[152:155], v166 offset:2048
	ds_read_b128 v[166:169], v166 offset:3072
	s_add_u32 s4, s34, s12
	s_addc_u32 s5, s35, s13
	s_mov_b32 m0, s11
	v_lshl_add_u64 v[186:187], s[4:5], 0, v[156:157]
	ds_read_b128 v[170:173], v194 offset:32768
	ds_read_b128 v[174:177], v194 offset:33792
	ds_read_b128 v[178:181], v194 offset:34816
	ds_read_b128 v[182:185], v194 offset:35840
	ds_read_b128 v[196:199], v194 offset:36864
	ds_read_b128 v[200:203], v194 offset:37888
	ds_read_b128 v[204:207], v194 offset:38912
	ds_read_b128 v[210:213], v194 offset:39936
	global_load_lds_dwordx4 v[186:187], off
	v_lshl_add_u64 v[186:187], s[4:5], 0, v[158:159]
	s_mov_b32 m0, s33
	s_nop 0
	global_load_lds_dwordx4 v[186:187], off
	s_waitcnt vmcnt(8)
	s_waitcnt lgkmcnt(0)
	s_barrier
	s_setprio 1
	s_waitcnt lgkmcnt(0)
	v_mfma_f32_16x16x32_bf16 v[124:127], v[128:131], v[170:173], v[124:127]
	v_mfma_f32_16x16x32_bf16 v[120:123], v[136:139], v[170:173], v[120:123]
	v_mfma_f32_16x16x32_bf16 v[108:111], v[128:131], v[178:181], v[108:111]
	v_mfma_f32_16x16x32_bf16 v[104:107], v[136:139], v[178:181], v[104:107]
	v_mfma_f32_16x16x32_bf16 v[92:95], v[128:131], v[196:199], v[92:95]
	v_mfma_f32_16x16x32_bf16 v[88:91], v[136:139], v[196:199], v[88:91]
	v_mfma_f32_16x16x32_bf16 v[76:79], v[128:131], v[204:207], v[76:79]
	v_mfma_f32_16x16x32_bf16 v[72:75], v[136:139], v[204:207], v[72:75]
	v_mfma_f32_16x16x32_bf16 v[124:127], v[132:135], v[174:177], v[124:127]
	v_mfma_f32_16x16x32_bf16 v[120:123], v[140:143], v[174:177], v[120:123]
	v_mfma_f32_16x16x32_bf16 v[108:111], v[132:135], v[182:185], v[108:111]
	v_mfma_f32_16x16x32_bf16 v[104:107], v[140:143], v[182:185], v[104:107]
	v_mfma_f32_16x16x32_bf16 v[92:95], v[132:135], v[200:203], v[92:95]
	v_mfma_f32_16x16x32_bf16 v[88:91], v[140:143], v[200:203], v[88:91]
	v_mfma_f32_16x16x32_bf16 v[76:79], v[132:135], v[210:213], v[76:79]
	v_mfma_f32_16x16x32_bf16 v[72:75], v[140:143], v[210:213], v[72:75]
	s_setprio 0
	s_setprio 1
	v_mfma_f32_16x16x32_bf16 v[116:119], v[144:147], v[170:173], v[116:119]
	v_mfma_f32_16x16x32_bf16 v[112:115], v[152:155], v[170:173], v[112:115]
	v_mfma_f32_16x16x32_bf16 v[100:103], v[144:147], v[178:181], v[100:103]
	v_mfma_f32_16x16x32_bf16 v[96:99], v[152:155], v[178:181], v[96:99]
	v_mfma_f32_16x16x32_bf16 v[84:87], v[144:147], v[196:199], v[84:87]
	v_mfma_f32_16x16x32_bf16 v[80:83], v[152:155], v[196:199], v[80:83]
	v_mfma_f32_16x16x32_bf16 v[68:71], v[144:147], v[204:207], v[68:71]
	v_mfma_f32_16x16x32_bf16 v[64:67], v[152:155], v[204:207], v[64:67]
	v_mfma_f32_16x16x32_bf16 v[116:119], v[148:151], v[174:177], v[116:119]
	v_mfma_f32_16x16x32_bf16 v[112:115], v[166:169], v[174:177], v[112:115]
	v_mfma_f32_16x16x32_bf16 v[100:103], v[148:151], v[182:185], v[100:103]
	v_mfma_f32_16x16x32_bf16 v[96:99], v[166:169], v[182:185], v[96:99]
	v_mfma_f32_16x16x32_bf16 v[84:87], v[148:151], v[200:203], v[84:87]
	v_mfma_f32_16x16x32_bf16 v[80:83], v[166:169], v[200:203], v[80:83]
	v_mfma_f32_16x16x32_bf16 v[68:71], v[148:151], v[210:213], v[68:71]
	v_mfma_f32_16x16x32_bf16 v[64:67], v[166:169], v[210:213], v[64:67]
	s_setprio 0
	s_barrier
; #define PG8_STAGE(bufoff, gbase, voff) do { _Pragma("unroll") for (int _i = 0; _i < 2; ++_i) \
;         __builtin_amdgcn_global_load_lds((const unsigned*)((const char*)(gbase) + (voff)[_i]), (PG8_LAS unsigned*)(lds + (bufoff) + ldsw + _i * 8192), 16, 0, 0); } while (0)
; #define PG8_LDA(dst, b, h) do { _Pragma("unroll") for (int m = 0; m < 4; ++m) _Pragma("unroll") for (int k = 0; k < 2; ++k) dst[m][k] = *(const PG8_LAS bf16x8*)(lds + PG8_SA(b, h) + aoff + m * 2048 + k * 1024); } while (0)
; #define PG8_MMA(ai, bj, At, Bt) do { __builtin_amdgcn_s_setprio(1); _Pragma("unroll") for (int m = 0; m < 4; ++m) _Pragma("unroll") for (int n = 0; n < 2; ++n) _Pragma("unroll") for (int k = 0; k < 2; ++k) \
;         acc[ai][bj][m][n] = __builtin_amdgcn_mfma_f32_16x16x32_bf16(Bt[n][k], At[m][k], acc[ai][bj][m][n], 0, 0, 0); __builtin_amdgcn_s_setprio(0); } while (0)
; #define PG8_WAIT_V(n) asm volatile("s_waitcnt vmcnt(" #n ")" ::: "memory")
; #define PG8_WAIT_L(n) asm volatile("s_waitcnt lgkmcnt(" #n ")" ::: "memory")
; #define PG8_BAR __builtin_amdgcn_s_barrier()
; #define PG8_SCHED __builtin_amdgcn_sched_barrier(0)
; template <class Epi, class Sched, bool ALIGN_EPI = false, bool SP2 = false>
; __device__ __forceinline__ void gemm_phase(PG8_LAS unsigned char* lds, const Gemm g, const Sched& S, const Epi& E, const int tid_in) {
;     ...
;         for (int t = 0; t < nt; t += 2) {
;     ...
;             PG8_LDA(At, 1, 1); PG8_STAGE(PG8_SB(1, 0), b3, voffB); PG8_STAGE(PG8_SB(1, 1), b3 + hstepB, voffB); PG8_STAGE(PG8_SA(1, 0), a3, voffA);
;             PG8_WAIT_V(8); PG8_WAIT_L(0); PG8_BAR; PG8_MMA(1, 0, At, B0); PG8_MMA(1, 1, At, B1); PG8_BAR; PG8_SCHED;
	s_add_u32 s4, s30, 0x4000
	s_addc_u32 s5, s31, 0
	s_add_i32 s30, s41, s0
	v_lshl_add_u64 v[186:187], s[4:5], 0, v[156:157]
	s_mov_b32 m0, s30
	ds_read_b128 v[170:173], v194 offset:49152
	ds_read_b128 v[174:177], v194 offset:50176
	ds_read_b128 v[178:181], v194 offset:51200
	ds_read_b128 v[182:185], v194 offset:52224
	ds_read_b128 v[196:199], v194 offset:53248
	ds_read_b128 v[200:203], v194 offset:54272
	ds_read_b128 v[204:207], v194 offset:55296
	ds_read_b128 v[210:213], v194 offset:56320
	global_load_lds_dwordx4 v[186:187], off
	s_add_i32 m0, s30, 0x2000
	v_lshl_add_u64 v[186:187], s[4:5], 0, v[158:159]
	s_add_u32 s4, s4, s12
	s_addc_u32 s5, s5, s13
	s_add_i32 s30, s64, s0
	global_load_lds_dwordx4 v[186:187], off
	v_lshl_add_u64 v[186:187], s[4:5], 0, v[156:157]
	s_mov_b32 m0, s30
	s_nop 0
	global_load_lds_dwordx4 v[186:187], off
	v_lshl_add_u64 v[186:187], s[4:5], 0, v[158:159]
	s_add_i32 m0, s30, 0x2000
	s_nop 0
	global_load_lds_dwordx4 v[186:187], off
	v_lshl_add_u64 v[186:187], s[28:29], 0, v[156:157]
	s_mov_b32 m0, s37
	s_nop 0
	global_load_lds_dwordx4 v[186:187], off
	v_lshl_add_u64 v[186:187], s[28:29], 0, v[158:159]
	s_mov_b32 m0, s42
	s_nop 0
	global_load_lds_dwordx4 v[186:187], off
	s_waitcnt vmcnt(8)
	s_waitcnt lgkmcnt(0)
	s_barrier
	s_setprio 1
	s_waitcnt lgkmcnt(0)
	v_mfma_f32_16x16x32_bf16 v[60:63], v[128:131], v[170:173], v[60:63]
	v_mfma_f32_16x16x32_bf16 v[56:59], v[136:139], v[170:173], v[56:59]
	v_mfma_f32_16x16x32_bf16 v[44:47], v[128:131], v[178:181], v[44:47]
	v_mfma_f32_16x16x32_bf16 v[40:43], v[136:139], v[178:181], v[40:43]
	v_mfma_f32_16x16x32_bf16 v[28:31], v[128:131], v[196:199], v[28:31]
	v_mfma_f32_16x16x32_bf16 v[24:27], v[136:139], v[196:199], v[24:27]
	v_mfma_f32_16x16x32_bf16 v[12:15], v[128:131], v[204:207], v[12:15]
	v_mfma_f32_16x16x32_bf16 v[8:11], v[136:139], v[204:207], v[8:11]
	v_mfma_f32_16x16x32_bf16 v[60:63], v[132:135], v[174:177], v[60:63]
	v_mfma_f32_16x16x32_bf16 v[56:59], v[140:143], v[174:177], v[56:59]
	v_mfma_f32_16x16x32_bf16 v[44:47], v[132:135], v[182:185], v[44:47]
	v_mfma_f32_16x16x32_bf16 v[40:43], v[140:143], v[182:185], v[40:43]
	v_mfma_f32_16x16x32_bf16 v[28:31], v[132:135], v[200:203], v[28:31]
	v_mfma_f32_16x16x32_bf16 v[24:27], v[140:143], v[200:203], v[24:27]
	v_mfma_f32_16x16x32_bf16 v[12:15], v[132:135], v[210:213], v[12:15]
	v_mfma_f32_16x16x32_bf16 v[8:11], v[140:143], v[210:213], v[8:11]
	s_setprio 0
	s_setprio 1
	v_mfma_f32_16x16x32_bf16 v[52:55], v[144:147], v[170:173], v[52:55]
	v_mfma_f32_16x16x32_bf16 v[48:51], v[152:155], v[170:173], v[48:51]
	v_mfma_f32_16x16x32_bf16 v[36:39], v[144:147], v[178:181], v[36:39]
	v_mfma_f32_16x16x32_bf16 v[32:35], v[152:155], v[178:181], v[32:35]
	v_mfma_f32_16x16x32_bf16 v[20:23], v[144:147], v[196:199], v[20:23]
	v_mfma_f32_16x16x32_bf16 v[16:19], v[152:155], v[196:199], v[16:19]
	v_mfma_f32_16x16x32_bf16 v[4:7], v[144:147], v[204:207], v[4:7]
	v_mfma_f32_16x16x32_bf16 v[0:3], v[152:155], v[204:207], v[0:3]
	v_mfma_f32_16x16x32_bf16 v[52:55], v[148:151], v[174:177], v[52:55]
	v_mfma_f32_16x16x32_bf16 v[48:51], v[166:169], v[174:177], v[48:51]
	v_mfma_f32_16x16x32_bf16 v[36:39], v[148:151], v[182:185], v[36:39]
	v_mfma_f32_16x16x32_bf16 v[32:35], v[166:169], v[182:185], v[32:35]
	v_mfma_f32_16x16x32_bf16 v[20:23], v[148:151], v[200:203], v[20:23]
	v_mfma_f32_16x16x32_bf16 v[16:19], v[166:169], v[200:203], v[16:19]
	v_mfma_f32_16x16x32_bf16 v[4:7], v[148:151], v[210:213], v[4:7]
	v_mfma_f32_16x16x32_bf16 v[0:3], v[166:169], v[210:213], v[0:3]
	s_setprio 0
	s_barrier
	s_add_u32 s26, s26, 0x8000
	s_addc_u32 s27, s27, 0
	s_add_u32 s6, s6, 0x8000
	s_addc_u32 s7, s7, 0
	s_cmp_ge_i32 s40, s10
	s_mov_b32 s28, s40
	s_cbranch_scc1 .LBB0_146
	.p2align	6

; #define PG8_STAGE(bufoff, gbase, voff) do { _Pragma("unroll") for (int _i = 0; _i < 2; ++_i) \
;         __builtin_amdgcn_global_load_lds((const unsigned*)((const char*)(gbase) + (voff)[_i]), (PG8_LAS unsigned*)(lds + (bufoff) + ldsw + _i * 8192), 16, 0, 0); } while (0)
; #define PG8_LDA(dst, b, h) do { _Pragma("unroll") for (int m = 0; m < 4; ++m) _Pragma("unroll") for (int k = 0; k < 2; ++k) dst[m][k] = *(const PG8_LAS bf16x8*)(lds + PG8_SA(b, h) + aoff + m * 2048 + k * 1024); } while (0)
; #define PG8_LDB(dst, b, h) do { _Pragma("unroll") for (int n = 0; n < 2; ++n) _Pragma("unroll") for (int k = 0; k < 2; ++k) dst[n][k] = *(const PG8_LAS bf16x8*)(lds + PG8_SB(b, h) + boff + n * 2048 + k * 1024); } while (0)
; #define PG8_MMA(ai, bj, At, Bt) do { __builtin_amdgcn_s_setprio(1); _Pragma("unroll") for (int m = 0; m < 4; ++m) _Pragma("unroll") for (int n = 0; n < 2; ++n) _Pragma("unroll") for (int k = 0; k < 2; ++k) \
;         acc[ai][bj][m][n] = __builtin_amdgcn_mfma_f32_16x16x32_bf16(Bt[n][k], At[m][k], acc[ai][bj][m][n], 0, 0, 0); __builtin_amdgcn_s_setprio(0); } while (0)
; #define PG8_WAIT_V(n) asm volatile("s_waitcnt vmcnt(" #n ")" ::: "memory")
; #define PG8_WAIT_L(n) asm volatile("s_waitcnt lgkmcnt(" #n ")" ::: "memory")
; template <class Epi, class Sched, bool ALIGN_EPI = false, bool SP2 = false>
; __device__ __forceinline__ void gemm_phase(PG8_LAS unsigned char* lds, const Gemm g, const Sched& S, const Epi& E, const int tid_in) {
;     ...
;             const bool last = (t == nt - 2);
;             const char* a1 = cA + (size_t)(t + 1) * kstepA;
;             const char* a2 = last ? nA : cA + (size_t)(t + 2) * kstepA; const char* b2 = last ? nB : cB + (size_t)(t + 2) * kstepB;
;             const char* a3 = a2 + kstepA; const char* b3 = b2 + kstepB;
;             if (last && has_next) S.a_ready(nxt);
;             if constexpr (SP2) {
;             PG8_LDB(B0, 0, 0); PG8_LDB(B1, 0, 1); PG8_SCHED; PG8_LDA(At, 0, 0); PG8_STAGE(PG8_SA(1, 1), a1 + hstepA, voffA);
;             PG8_WAIT_V(8); PG8_WAIT_L(0); PG8_BAR; PG8_MMA(0, 0, At, B0); PG8_MMA(0, 1, At, B1); PG8_BAR; PG8_SCHED;
;             PG8_LDA(At, 0, 1); PG8_STAGE(PG8_SB(0, 0), b2, voffB); PG8_STAGE(PG8_SB(0, 1), b2 + hstepB, voffB); PG8_STAGE(PG8_SA(0, 0), a2, voffA);
;             PG8_WAIT_V(8); PG8_WAIT_L(0); PG8_BAR; PG8_MMA(1, 0, At, B0); PG8_MMA(1, 1, At, B1); PG8_BAR; PG8_SCHED;
.LBB0_232:
	s_andn2_b64 vcc, exec, s[26:27]
	s_cbranch_vccnz .Lzero_acc_3
	s_add_u32 s78, s46, s18
	s_addc_u32 s96, s47, s19
	s_add_u32 s97, s48, 0x8000
	s_addc_u32 s6, s49, 0
	s_mov_b64 s[42:43], 0
	s_add_u32 s4, s42, 1
	s_addc_u32 s5, s43, 0
	s_add_u32 s44, s42, 2
	s_addc_u32 s45, s43, 0
	s_lshl_b64 s[48:49], s[44:45], s70
	s_add_u32 s7, s46, s48
	s_addc_u32 s43, s47, s49
	s_cmp_eq_u32 s52, s42
	s_cselect_b32 vcc_lo, s62, s7
	s_cselect_b32 vcc_hi, s63, s43
	s_cselect_b32 s48, s36, s97
	s_cselect_b32 s49, s37, s6
	s_add_u32 s42, vcc_lo, s91
	s_addc_u32 s43, vcc_hi, 0
	s_add_i32 s7, 0, 0x10000
	s_add_i32 s74, 0, 0x14000
	v_add_u32_e32 v108, s7, v244
	v_add_u32_e32 v156, s74, v244
	ds_read_b128 v[64:67], v108
	ds_read_b128 v[76:79], v108 offset:1024
	ds_read_b128 v[88:91], v108 offset:2048
	ds_read_b128 v[108:111], v108 offset:3072
	ds_read_b128 v[144:147], v156
	ds_read_b128 v[148:151], v156 offset:1024
	ds_read_b128 v[152:155], v156 offset:2048
	ds_read_b128 v[156:159], v156 offset:3072
	s_lshl_b64 s[4:5], s[4:5], s70
	s_add_u32 s4, s78, s4
	s_addc_u32 s5, s96, s5
	v_lshl_add_u64 v[192:193], s[4:5], 0, v[210:211]
	s_add_i32 m0, s13, 0xc000
	ds_read_b128 v[160:163], v248
	ds_read_b128 v[164:167], v248 offset:1024
	ds_read_b128 v[168:171], v248 offset:2048
	ds_read_b128 v[172:175], v248 offset:3072
	ds_read_b128 v[176:179], v248 offset:4096
	ds_read_b128 v[180:183], v248 offset:5120
	ds_read_b128 v[184:187], v248 offset:6144
	ds_read_b128 v[188:191], v248 offset:7168
	global_load_lds_dwordx4 v[192:193], off
	v_lshl_add_u64 v[192:193], s[4:5], 0, v[214:215]
	s_add_i32 m0, s13, 0xe000
	s_nop 0
	global_load_lds_dwordx4 v[192:193], off
	s_waitcnt vmcnt(8)
	s_waitcnt lgkmcnt(0)
	s_barrier
	s_setprio 1
	s_waitcnt lgkmcnt(0)
	v_mfma_f32_16x16x32_bf16 v[140:143], v[64:67], v[160:163], 0
	v_mfma_f32_16x16x32_bf16 v[136:139], v[88:91], v[160:163], 0
	v_mfma_f32_16x16x32_bf16 v[124:127], v[64:67], v[168:171], 0
	v_mfma_f32_16x16x32_bf16 v[120:123], v[88:91], v[168:171], 0
	v_mfma_f32_16x16x32_bf16 v[104:107], v[64:67], v[176:179], 0
	v_mfma_f32_16x16x32_bf16 v[100:103], v[88:91], v[176:179], 0
	v_mfma_f32_16x16x32_bf16 v[84:87], v[64:67], v[184:187], 0
	v_mfma_f32_16x16x32_bf16 v[80:83], v[88:91], v[184:187], 0
	v_mfma_f32_16x16x32_bf16 v[140:143], v[76:79], v[164:167], v[140:143]
	v_mfma_f32_16x16x32_bf16 v[136:139], v[108:111], v[164:167], v[136:139]
	v_mfma_f32_16x16x32_bf16 v[124:127], v[76:79], v[172:175], v[124:127]
	v_mfma_f32_16x16x32_bf16 v[120:123], v[108:111], v[172:175], v[120:123]
	v_mfma_f32_16x16x32_bf16 v[104:107], v[76:79], v[180:183], v[104:107]
	v_mfma_f32_16x16x32_bf16 v[100:103], v[108:111], v[180:183], v[100:103]
	v_mfma_f32_16x16x32_bf16 v[84:87], v[76:79], v[188:191], v[84:87]
	v_mfma_f32_16x16x32_bf16 v[80:83], v[108:111], v[188:191], v[80:83]
	s_setprio 0
	s_setprio 1
	v_mfma_f32_16x16x32_bf16 v[132:135], v[144:147], v[160:163], 0
	v_mfma_f32_16x16x32_bf16 v[128:131], v[152:155], v[160:163], 0
	v_mfma_f32_16x16x32_bf16 v[116:119], v[144:147], v[168:171], 0
	v_mfma_f32_16x16x32_bf16 v[112:115], v[152:155], v[168:171], 0
	v_mfma_f32_16x16x32_bf16 v[96:99], v[144:147], v[176:179], 0
	v_mfma_f32_16x16x32_bf16 v[92:95], v[152:155], v[176:179], 0
	v_mfma_f32_16x16x32_bf16 v[72:75], v[144:147], v[184:187], 0
	v_mfma_f32_16x16x32_bf16 v[68:71], v[152:155], v[184:187], 0
	v_mfma_f32_16x16x32_bf16 v[132:135], v[148:151], v[164:167], v[132:135]
	v_mfma_f32_16x16x32_bf16 v[128:131], v[156:159], v[164:167], v[128:131]
	v_mfma_f32_16x16x32_bf16 v[116:119], v[148:151], v[172:175], v[116:119]
	v_mfma_f32_16x16x32_bf16 v[112:115], v[156:159], v[172:175], v[112:115]
	v_mfma_f32_16x16x32_bf16 v[96:99], v[148:151], v[180:183], v[96:99]
	v_mfma_f32_16x16x32_bf16 v[92:95], v[156:159], v[180:183], v[92:95]
	v_mfma_f32_16x16x32_bf16 v[72:75], v[148:151], v[188:191], v[72:75]
	v_mfma_f32_16x16x32_bf16 v[68:71], v[156:159], v[188:191], v[68:71]
	s_setprio 0
	s_barrier
	s_add_i32 s4, s7, s50
	v_lshl_add_u64 v[192:193], s[48:49], 0, v[208:209]
	s_mov_b32 m0, s4
	ds_read_b128 v[160:163], v248 offset:16384
	ds_read_b128 v[164:167], v248 offset:17408
	ds_read_b128 v[168:171], v248 offset:18432
	ds_read_b128 v[172:175], v248 offset:19456
	ds_read_b128 v[176:179], v248 offset:20480
	ds_read_b128 v[180:183], v248 offset:21504
	ds_read_b128 v[184:187], v248 offset:22528
	ds_read_b128 v[188:191], v248 offset:23552
	global_load_lds_dwordx4 v[192:193], off
	s_add_i32 m0, s4, 0x2000
	s_add_u32 s4, s48, s14
	v_lshl_add_u64 v[192:193], s[48:49], 0, v[212:213]
	s_addc_u32 s5, s49, s15
	s_add_i32 s7, s74, s50
	global_load_lds_dwordx4 v[192:193], off
	v_lshl_add_u64 v[192:193], s[4:5], 0, v[208:209]
	s_mov_b32 m0, s7
	s_nop 0
	global_load_lds_dwordx4 v[192:193], off
	v_lshl_add_u64 v[192:193], s[4:5], 0, v[212:213]
	s_add_i32 m0, s7, 0x2000
	s_nop 0
	global_load_lds_dwordx4 v[192:193], off
	v_lshl_add_u64 v[192:193], vcc, 0, v[210:211]
	s_mov_b32 m0, s13
	s_nop 0
	global_load_lds_dwordx4 v[192:193], off
	v_lshl_add_u64 v[192:193], vcc, 0, v[214:215]
	s_mov_b32 m0, s51
	s_nop 0
	global_load_lds_dwordx4 v[192:193], off
	s_waitcnt vmcnt(8)
	s_waitcnt lgkmcnt(0)
	s_barrier
; #define PG8_STAGE(bufoff, gbase, voff) do { _Pragma("unroll") for (int _i = 0; _i < 2; ++_i) \
;         __builtin_amdgcn_global_load_lds((const unsigned*)((const char*)(gbase) + (voff)[_i]), (PG8_LAS unsigned*)(lds + (bufoff) + ldsw + _i * 8192), 16, 0, 0); } while (0)
; #define PG8_LDA(dst, b, h) do { _Pragma("unroll") for (int m = 0; m < 4; ++m) _Pragma("unroll") for (int k = 0; k < 2; ++k) dst[m][k] = *(const PG8_LAS bf16x8*)(lds + PG8_SA(b, h) + aoff + m * 2048 + k * 1024); } while (0)
; #define PG8_LDB(dst, b, h) do { _Pragma("unroll") for (int n = 0; n < 2; ++n) _Pragma("unroll") for (int k = 0; k < 2; ++k) dst[n][k] = *(const PG8_LAS bf16x8*)(lds + PG8_SB(b, h) + boff + n * 2048 + k * 1024); } while (0)
; #define PG8_MMA(ai, bj, At, Bt) do { __builtin_amdgcn_s_setprio(1); _Pragma("unroll") for (int m = 0; m < 4; ++m) _Pragma("unroll") for (int n = 0; n < 2; ++n) _Pragma("unroll") for (int k = 0; k < 2; ++k) \
;         acc[ai][bj][m][n] = __builtin_amdgcn_mfma_f32_16x16x32_bf16(Bt[n][k], At[m][k], acc[ai][bj][m][n], 0, 0, 0); __builtin_amdgcn_s_setprio(0); } while (0)
; #define PG8_WAIT_V(n) asm volatile("s_waitcnt vmcnt(" #n ")" ::: "memory")
; #define PG8_WAIT_L(n) asm volatile("s_waitcnt lgkmcnt(" #n ")" ::: "memory")
; #define PG8_BAR __builtin_amdgcn_s_barrier()
; #define PG8_SCHED __builtin_amdgcn_sched_barrier(0)
; template <class Epi, class Sched, bool ALIGN_EPI = false, bool SP2 = false>
; __device__ __forceinline__ void gemm_phase(PG8_LAS unsigned char* lds, const Gemm g, const Sched& S, const Epi& E, const int tid_in) {
;     ...
;             PG8_WAIT_V(8); PG8_WAIT_L(0); PG8_BAR; PG8_MMA(1, 0, At, B0); PG8_MMA(1, 1, At, B1); PG8_BAR; PG8_SCHED;
;             PG8_LDB(B0, 1, 0); PG8_LDB(B1, 1, 1); PG8_SCHED; PG8_LDA(At, 1, 0); PG8_STAGE(PG8_SA(0, 1), a2 + hstepA, voffA);
;             PG8_WAIT_V(8); PG8_WAIT_L(0); PG8_BAR; PG8_MMA(0, 0, At, B0); PG8_MMA(0, 1, At, B1); PG8_BAR; PG8_SCHED;
	s_setprio 1
	s_waitcnt lgkmcnt(0)
	v_mfma_f32_16x16x32_bf16 v[60:63], v[64:67], v[160:163], 0
	v_mfma_f32_16x16x32_bf16 v[56:59], v[88:91], v[160:163], 0
	v_mfma_f32_16x16x32_bf16 v[44:47], v[64:67], v[168:171], 0
	v_mfma_f32_16x16x32_bf16 v[40:43], v[88:91], v[168:171], 0
	v_mfma_f32_16x16x32_bf16 v[28:31], v[64:67], v[176:179], 0
	v_mfma_f32_16x16x32_bf16 v[24:27], v[88:91], v[176:179], 0
	v_mfma_f32_16x16x32_bf16 v[12:15], v[64:67], v[184:187], 0
	v_mfma_f32_16x16x32_bf16 v[8:11], v[88:91], v[184:187], 0
	v_mfma_f32_16x16x32_bf16 v[60:63], v[76:79], v[164:167], v[60:63]
	v_mfma_f32_16x16x32_bf16 v[56:59], v[108:111], v[164:167], v[56:59]
	v_mfma_f32_16x16x32_bf16 v[44:47], v[76:79], v[172:175], v[44:47]
	v_mfma_f32_16x16x32_bf16 v[40:43], v[108:111], v[172:175], v[40:43]
	v_mfma_f32_16x16x32_bf16 v[28:31], v[76:79], v[180:183], v[28:31]
	v_mfma_f32_16x16x32_bf16 v[24:27], v[108:111], v[180:183], v[24:27]
	v_mfma_f32_16x16x32_bf16 v[12:15], v[76:79], v[188:191], v[12:15]
	v_mfma_f32_16x16x32_bf16 v[8:11], v[108:111], v[188:191], v[8:11]
	s_setprio 0
	s_setprio 1
	v_mfma_f32_16x16x32_bf16 v[52:55], v[144:147], v[160:163], 0
	v_mfma_f32_16x16x32_bf16 v[48:51], v[152:155], v[160:163], 0
	v_mfma_f32_16x16x32_bf16 v[36:39], v[144:147], v[168:171], 0
	v_mfma_f32_16x16x32_bf16 v[32:35], v[152:155], v[168:171], 0
	v_mfma_f32_16x16x32_bf16 v[20:23], v[144:147], v[176:179], 0
	v_mfma_f32_16x16x32_bf16 v[16:19], v[152:155], v[176:179], 0
	v_mfma_f32_16x16x32_bf16 v[4:7], v[144:147], v[184:187], 0
	v_mfma_f32_16x16x32_bf16 v[0:3], v[152:155], v[184:187], 0
	v_mfma_f32_16x16x32_bf16 v[52:55], v[148:151], v[164:167], v[52:55]
	v_mfma_f32_16x16x32_bf16 v[48:51], v[156:159], v[164:167], v[48:51]
	v_mfma_f32_16x16x32_bf16 v[36:39], v[148:151], v[172:175], v[36:39]
	v_mfma_f32_16x16x32_bf16 v[32:35], v[156:159], v[172:175], v[32:35]
	v_mfma_f32_16x16x32_bf16 v[20:23], v[148:151], v[180:183], v[20:23]
	v_mfma_f32_16x16x32_bf16 v[16:19], v[156:159], v[180:183], v[16:19]
	v_mfma_f32_16x16x32_bf16 v[4:7], v[148:151], v[188:191], v[4:7]
	v_mfma_f32_16x16x32_bf16 v[0:3], v[156:159], v[188:191], v[0:3]
	s_setprio 0
	s_barrier
	s_add_i32 s7, 0, 0x18000
	s_add_i32 s74, 0, 0x1c000
	v_add_u32_e32 v108, s7, v244
	v_add_u32_e32 v156, s74, v244
	ds_read_b128 v[64:67], v108
	ds_read_b128 v[76:79], v108 offset:1024
	ds_read_b128 v[88:91], v108 offset:2048
	ds_read_b128 v[108:111], v108 offset:3072
	ds_read_b128 v[144:147], v156
	ds_read_b128 v[148:151], v156 offset:1024
	ds_read_b128 v[152:155], v156 offset:2048
	ds_read_b128 v[156:159], v156 offset:3072
	s_add_u32 s4, vcc_lo, s18
	s_addc_u32 s5, vcc_hi, s19
	s_mov_b32 m0, s64
	v_lshl_add_u64 v[192:193], s[4:5], 0, v[210:211]
	ds_read_b128 v[160:163], v248 offset:32768
	ds_read_b128 v[164:167], v248 offset:33792
	ds_read_b128 v[168:171], v248 offset:34816
	ds_read_b128 v[172:175], v248 offset:35840
	ds_read_b128 v[176:179], v248 offset:36864
	ds_read_b128 v[180:183], v248 offset:37888
	ds_read_b128 v[184:187], v248 offset:38912
	ds_read_b128 v[188:191], v248 offset:39936
	global_load_lds_dwordx4 v[192:193], off
	v_lshl_add_u64 v[192:193], s[4:5], 0, v[214:215]
	s_mov_b32 m0, s86
	s_nop 0
	global_load_lds_dwordx4 v[192:193], off
	s_waitcnt vmcnt(8)
	s_waitcnt lgkmcnt(0)
	s_barrier
	s_setprio 1
	s_waitcnt lgkmcnt(0)
	v_mfma_f32_16x16x32_bf16 v[140:143], v[64:67], v[160:163], v[140:143]
	v_mfma_f32_16x16x32_bf16 v[136:139], v[88:91], v[160:163], v[136:139]
	v_mfma_f32_16x16x32_bf16 v[124:127], v[64:67], v[168:171], v[124:127]
	v_mfma_f32_16x16x32_bf16 v[120:123], v[88:91], v[168:171], v[120:123]
	v_mfma_f32_16x16x32_bf16 v[104:107], v[64:67], v[176:179], v[104:107]
	v_mfma_f32_16x16x32_bf16 v[100:103], v[88:91], v[176:179], v[100:103]
	v_mfma_f32_16x16x32_bf16 v[84:87], v[64:67], v[184:187], v[84:87]
	v_mfma_f32_16x16x32_bf16 v[80:83], v[88:91], v[184:187], v[80:83]
	v_mfma_f32_16x16x32_bf16 v[140:143], v[76:79], v[164:167], v[140:143]
	v_mfma_f32_16x16x32_bf16 v[136:139], v[108:111], v[164:167], v[136:139]
	v_mfma_f32_16x16x32_bf16 v[124:127], v[76:79], v[172:175], v[124:127]
	v_mfma_f32_16x16x32_bf16 v[120:123], v[108:111], v[172:175], v[120:123]
	v_mfma_f32_16x16x32_bf16 v[104:107], v[76:79], v[180:183], v[104:107]
	v_mfma_f32_16x16x32_bf16 v[100:103], v[108:111], v[180:183], v[100:103]
	v_mfma_f32_16x16x32_bf16 v[84:87], v[76:79], v[188:191], v[84:87]
	v_mfma_f32_16x16x32_bf16 v[80:83], v[108:111], v[188:191], v[80:83]
	s_setprio 0
	s_setprio 1
	v_mfma_f32_16x16x32_bf16 v[132:135], v[144:147], v[160:163], v[132:135]
	v_mfma_f32_16x16x32_bf16 v[128:131], v[152:155], v[160:163], v[128:131]
	v_mfma_f32_16x16x32_bf16 v[116:119], v[144:147], v[168:171], v[116:119]
	v_mfma_f32_16x16x32_bf16 v[112:115], v[152:155], v[168:171], v[112:115]
	v_mfma_f32_16x16x32_bf16 v[96:99], v[144:147], v[176:179], v[96:99]
	v_mfma_f32_16x16x32_bf16 v[92:95], v[152:155], v[176:179], v[92:95]
	v_mfma_f32_16x16x32_bf16 v[72:75], v[144:147], v[184:187], v[72:75]
	v_mfma_f32_16x16x32_bf16 v[68:71], v[152:155], v[184:187], v[68:71]
	v_mfma_f32_16x16x32_bf16 v[132:135], v[148:151], v[164:167], v[132:135]
	v_mfma_f32_16x16x32_bf16 v[128:131], v[156:159], v[164:167], v[128:131]
	v_mfma_f32_16x16x32_bf16 v[116:119], v[148:151], v[172:175], v[116:119]
	v_mfma_f32_16x16x32_bf16 v[112:115], v[156:159], v[172:175], v[112:115]
	v_mfma_f32_16x16x32_bf16 v[96:99], v[148:151], v[180:183], v[96:99]
	v_mfma_f32_16x16x32_bf16 v[92:95], v[156:159], v[180:183], v[92:95]
	v_mfma_f32_16x16x32_bf16 v[72:75], v[148:151], v[188:191], v[72:75]
	v_mfma_f32_16x16x32_bf16 v[68:71], v[156:159], v[188:191], v[68:71]
	s_setprio 0
	s_barrier
; #define PG8_STAGE(bufoff, gbase, voff) do { _Pragma("unroll") for (int _i = 0; _i < 2; ++_i) \
;         __builtin_amdgcn_global_load_lds((const unsigned*)((const char*)(gbase) + (voff)[_i]), (PG8_LAS unsigned*)(lds + (bufoff) + ldsw + _i * 8192), 16, 0, 0); } while (0)
; #define PG8_LDA(dst, b, h) do { _Pragma("unroll") for (int m = 0; m < 4; ++m) _Pragma("unroll") for (int k = 0; k < 2; ++k) dst[m][k] = *(const PG8_LAS bf16x8*)(lds + PG8_SA(b, h) + aoff + m * 2048 + k * 1024); } while (0)
; #define PG8_MMA(ai, bj, At, Bt) do { __builtin_amdgcn_s_setprio(1); _Pragma("unroll") for (int m = 0; m < 4; ++m) _Pragma("unroll") for (int n = 0; n < 2; ++n) _Pragma("unroll") for (int k = 0; k < 2; ++k) \
;         acc[ai][bj][m][n] = __builtin_amdgcn_mfma_f32_16x16x32_bf16(Bt[n][k], At[m][k], acc[ai][bj][m][n], 0, 0, 0); __builtin_amdgcn_s_setprio(0); } while (0)
; #define PG8_WAIT_V(n) asm volatile("s_waitcnt vmcnt(" #n ")" ::: "memory")
; #define PG8_WAIT_L(n) asm volatile("s_waitcnt lgkmcnt(" #n ")" ::: "memory")
; #define PG8_BAR __builtin_amdgcn_s_barrier()
; #define PG8_SCHED __builtin_amdgcn_sched_barrier(0)
; template <class Epi, class Sched, bool ALIGN_EPI = false, bool SP2 = false>
; __device__ __forceinline__ void gemm_phase(PG8_LAS unsigned char* lds, const Gemm g, const Sched& S, const Epi& E, const int tid_in) {
;     ...
;         for (int t = 0; t < nt; t += 2) {
;     ...
;             PG8_LDA(At, 1, 1); PG8_STAGE(PG8_SB(1, 0), b3, voffB); PG8_STAGE(PG8_SB(1, 1), b3 + hstepB, voffB); PG8_STAGE(PG8_SA(1, 0), a3, voffA);
;             PG8_WAIT_V(8); PG8_WAIT_L(0); PG8_BAR; PG8_MMA(1, 0, At, B0); PG8_MMA(1, 1, At, B1); PG8_BAR; PG8_SCHED;
	s_add_u32 s4, s48, 0x4000
	s_addc_u32 s5, s49, 0
	s_add_i32 s7, s7, s50
	v_lshl_add_u64 v[192:193], s[4:5], 0, v[208:209]
	s_mov_b32 m0, s7
	ds_read_b128 v[160:163], v248 offset:49152
	ds_read_b128 v[164:167], v248 offset:50176
	ds_read_b128 v[168:171], v248 offset:51200
	ds_read_b128 v[172:175], v248 offset:52224
	ds_read_b128 v[176:179], v248 offset:53248
	ds_read_b128 v[180:183], v248 offset:54272
	ds_read_b128 v[184:187], v248 offset:55296
	ds_read_b128 v[188:191], v248 offset:56320
	global_load_lds_dwordx4 v[192:193], off
	s_add_i32 m0, s7, 0x2000
	v_lshl_add_u64 v[192:193], s[4:5], 0, v[212:213]
	s_add_u32 s4, s4, s14
	s_addc_u32 s5, s5, s15
	s_add_i32 s7, s74, s50
	global_load_lds_dwordx4 v[192:193], off
	v_lshl_add_u64 v[192:193], s[4:5], 0, v[208:209]
	s_mov_b32 m0, s7
	s_nop 0
	global_load_lds_dwordx4 v[192:193], off
	v_lshl_add_u64 v[192:193], s[4:5], 0, v[212:213]
	s_add_i32 m0, s7, 0x2000
	s_nop 0
	global_load_lds_dwordx4 v[192:193], off
	v_lshl_add_u64 v[192:193], s[42:43], 0, v[210:211]
	s_mov_b32 m0, s68
	s_nop 0
	global_load_lds_dwordx4 v[192:193], off
	v_lshl_add_u64 v[192:193], s[42:43], 0, v[214:215]
	s_mov_b32 m0, s69
	s_nop 0
	global_load_lds_dwordx4 v[192:193], off
	s_waitcnt vmcnt(8)
	s_waitcnt lgkmcnt(0)
	s_barrier
	s_setprio 1
	s_waitcnt lgkmcnt(0)
	v_mfma_f32_16x16x32_bf16 v[60:63], v[64:67], v[160:163], v[60:63]
	v_mfma_f32_16x16x32_bf16 v[56:59], v[88:91], v[160:163], v[56:59]
	v_mfma_f32_16x16x32_bf16 v[44:47], v[64:67], v[168:171], v[44:47]
	v_mfma_f32_16x16x32_bf16 v[40:43], v[88:91], v[168:171], v[40:43]
	v_mfma_f32_16x16x32_bf16 v[28:31], v[64:67], v[176:179], v[28:31]
	v_mfma_f32_16x16x32_bf16 v[24:27], v[88:91], v[176:179], v[24:27]
	v_mfma_f32_16x16x32_bf16 v[12:15], v[64:67], v[184:187], v[12:15]
	v_mfma_f32_16x16x32_bf16 v[8:11], v[88:91], v[184:187], v[8:11]
	v_mfma_f32_16x16x32_bf16 v[60:63], v[76:79], v[164:167], v[60:63]
	v_mfma_f32_16x16x32_bf16 v[56:59], v[108:111], v[164:167], v[56:59]
	v_mfma_f32_16x16x32_bf16 v[44:47], v[76:79], v[172:175], v[44:47]
	v_mfma_f32_16x16x32_bf16 v[40:43], v[108:111], v[172:175], v[40:43]
	v_mfma_f32_16x16x32_bf16 v[28:31], v[76:79], v[180:183], v[28:31]
	v_mfma_f32_16x16x32_bf16 v[24:27], v[108:111], v[180:183], v[24:27]
	v_mfma_f32_16x16x32_bf16 v[12:15], v[76:79], v[188:191], v[12:15]
	v_mfma_f32_16x16x32_bf16 v[8:11], v[108:111], v[188:191], v[8:11]
	s_setprio 0
	s_setprio 1
	v_mfma_f32_16x16x32_bf16 v[52:55], v[144:147], v[160:163], v[52:55]
	v_mfma_f32_16x16x32_bf16 v[48:51], v[152:155], v[160:163], v[48:51]
	v_mfma_f32_16x16x32_bf16 v[36:39], v[144:147], v[168:171], v[36:39]
	v_mfma_f32_16x16x32_bf16 v[32:35], v[152:155], v[168:171], v[32:35]
	v_mfma_f32_16x16x32_bf16 v[20:23], v[144:147], v[176:179], v[20:23]
	v_mfma_f32_16x16x32_bf16 v[16:19], v[152:155], v[176:179], v[16:19]
	v_mfma_f32_16x16x32_bf16 v[4:7], v[144:147], v[184:187], v[4:7]
	v_mfma_f32_16x16x32_bf16 v[0:3], v[152:155], v[184:187], v[0:3]
	v_mfma_f32_16x16x32_bf16 v[52:55], v[148:151], v[164:167], v[52:55]
	v_mfma_f32_16x16x32_bf16 v[48:51], v[156:159], v[164:167], v[48:51]
	v_mfma_f32_16x16x32_bf16 v[36:39], v[148:151], v[172:175], v[36:39]
	v_mfma_f32_16x16x32_bf16 v[32:35], v[156:159], v[172:175], v[32:35]
	v_mfma_f32_16x16x32_bf16 v[20:23], v[148:151], v[180:183], v[20:23]
	v_mfma_f32_16x16x32_bf16 v[16:19], v[156:159], v[180:183], v[16:19]
	v_mfma_f32_16x16x32_bf16 v[4:7], v[148:151], v[188:191], v[4:7]
	v_mfma_f32_16x16x32_bf16 v[0:3], v[156:159], v[188:191], v[0:3]
	s_setprio 0
	s_barrier
	s_add_u32 s97, s97, 0x8000
	s_addc_u32 s6, s6, 0
	s_cmp_ge_i32 s44, s12
	s_mov_b64 s[42:43], s[44:45]
	s_cbranch_scc1 .LBB0_235
	.p2align	6
